# W_in forget-gate tile epilogue: the 8 rows' ssq loads issued 4 rows ahead with counted waits (was one full drain per row)
# baseline (speedup 1.0000x reference)
; __device__ __forceinline__ float logsig_f(float x) { return fminf(x, 0.f) - __logf(1.f + __expf(-fabsf(x))); }
;     __device__ __forceinline__ void operator()(const f32x4 (&acc)[2][2][4][2], const pg8::Unit& u, int wr, int wc, int fr, int fq) const {
;     ...
;         if (pn == 14) {
;             if (wc == 0 && fq == 0) {
;                 const f32x4 fb0 = *(const f32x4*)fbias, fb1 = *(const f32x4*)(fbias + 4);
; #pragma unroll
;                 for (int ai = 0; ai < 2; ++ai)
; #pragma unroll
;                     for (int m = 0; m < 4; ++m) {
;                         const int row = row0 + ai * 128 + m * 16;
;                         const f32x4 sv = *(const f32x4*)(ssq + (size_t)row * 16), sv1 = *(const f32x4*)(ssq + (size_t)row * 16 + 4), sv2 = *(const f32x4*)(ssq + (size_t)row * 16 + 8), sv3 = *(const f32x4*)(ssq + (size_t)row * 16 + 12);
;                         const float st = ((sv[0] + sv[1]) + (sv[2] + sv[3])) + ((sv1[0] + sv1[1]) + (sv1[2] + sv1[3])) + ((sv2[0] + sv2[1]) + (sv2[2] + sv2[3])) + ((sv3[0] + sv3[1]) + (sv3[2] + sv3[3]));
;                         const float rs = __builtin_amdgcn_rsqf(st * (1.f / DM) + EPS);
;                         f32x4 a = acc[ai][0][m][0] * rs, b = acc[ai][0][m][1] * rs;
; #pragma unroll
;                         for (int i = 0; i < 4; ++i) { a[i] = logsig_f(a[i] + fb0[i]) * LOG2E; b[i] = logsig_f(b[i] + fb1[i]) * LOG2E; }
;                         *(f32x4*)(FF + (size_t)row * 8) = a; *(f32x4*)(FF + (size_t)row * 8 + 4) = b;
;                         asm volatile("" ::: "memory");
.LBB0_420:
	s_and_saveexec_b64 s[10:11], s[38:39]
	s_cbranch_execz .LBB0_422
	v_ashrrev_i32_e32 v167, 31, v166
	v_lshlrev_b64 v[72:73], 6, v[166:167]
	v_lshl_add_u64 v[84:85], s[82:83], 0, v[72:73]
	global_load_dwordx4 v[64:67], v193, s[34:35] offset:16
	global_load_dwordx4 v[68:71], v193, s[34:35]
	v_lshl_add_u64 v[218:219], s[82:83], 0, v[72:73]
	v_mov_b32_e32 v222, 0x2000
	v_mov_b32_e32 v223, 0
	v_lshl_add_u64 v[220:221], v[218:219], 0, v[222:223]
	global_load_dwordx4 v[128:131], v[218:219], off
	global_load_dwordx4 v[132:135], v[218:219], off offset:16
	global_load_dwordx4 v[136:139], v[218:219], off offset:32
	global_load_dwordx4 v[140:143], v[218:219], off offset:48
	global_load_dwordx4 v[144:147], v[218:219], off offset:1024
	global_load_dwordx4 v[148:151], v[218:219], off offset:1040
	global_load_dwordx4 v[168:171], v[218:219], off offset:1056
	global_load_dwordx4 v[176:179], v[218:219], off offset:1072
	global_load_dwordx4 v[180:183], v[218:219], off offset:2048
	global_load_dwordx4 v[184:187], v[218:219], off offset:2064
	global_load_dwordx4 v[188:191], v[218:219], off offset:2080
	global_load_dwordx4 v[204:207], v[218:219], off offset:2096
	global_load_dwordx4 v[208:211], v[218:219], off offset:3072
	global_load_dwordx4 v[224:227], v[218:219], off offset:3088
	global_load_dwordx4 v[228:231], v[218:219], off offset:3104
	global_load_dwordx4 v[232:235], v[218:219], off offset:3120
	s_nop 0
	s_mov_b32 s2, 0x3fb8aa3b
	s_waitcnt vmcnt(12)
	v_mov_b32_e32 v72, v128
	v_mov_b32_e32 v73, v129
	v_mov_b32_e32 v74, v130
	v_mov_b32_e32 v75, v131
	v_mov_b32_e32 v76, v132
	v_mov_b32_e32 v77, v133
	v_mov_b32_e32 v78, v134
	v_mov_b32_e32 v79, v135
	v_mov_b32_e32 v80, v136
	v_mov_b32_e32 v81, v137
	v_mov_b32_e32 v82, v138
	v_mov_b32_e32 v83, v139
	v_mov_b32_e32 v84, v140
	v_mov_b32_e32 v85, v141
	v_mov_b32_e32 v86, v142
	v_mov_b32_e32 v87, v143
	v_mov_b32_e32 v88, v73
	v_mov_b32_e32 v89, v74
	v_mov_b32_e32 v73, v75
	v_mov_b32_e32 v74, v77
	v_mov_b32_e32 v75, v78
	v_mov_b32_e32 v77, v79
	v_pk_add_f32 v[72:73], v[88:89], v[72:73]
	v_pk_add_f32 v[74:75], v[74:75], v[76:77]
	v_pk_add_f32 v[72:73], v[72:73], v[72:73] op_sel:[0,1] op_sel_hi:[1,0]
	v_pk_add_f32 v[74:75], v[74:75], v[74:75] op_sel:[0,1] op_sel_hi:[1,0]
	v_add_f32_e32 v76, v80, v81
	v_add_f32_e32 v78, v82, v83
	v_mov_b32_e32 v73, v84
	v_mov_b32_e32 v75, v85
	v_mov_b32_e32 v77, v86
	v_mov_b32_e32 v79, v87
	v_pk_add_f32 v[72:73], v[72:73], v[74:75]
	v_pk_add_f32 v[74:75], v[76:77], v[78:79]
	s_nop 0
	v_pk_add_f32 v[72:73], v[72:73], v[74:75]
	s_nop 0
	v_add_f32_e32 v72, v72, v73
	v_fmamk_f32 v72, v72, 0x3a800000, v212
	v_rsq_f32_e32 v72, v72
	global_load_dwordx4 v[128:131], v[220:221], off
	global_load_dwordx4 v[132:135], v[220:221], off offset:16
	global_load_dwordx4 v[136:139], v[220:221], off offset:32
	global_load_dwordx4 v[140:143], v[220:221], off offset:48
	v_pk_mul_f32 v[60:61], v[60:61], v[72:73] op_sel_hi:[1,0]
	v_pk_mul_f32 v[74:75], v[62:63], v[72:73] op_sel_hi:[1,0]
	v_pk_mul_f32 v[58:59], v[58:59], v[72:73] op_sel_hi:[1,0]
	v_pk_mul_f32 v[72:73], v[56:57], v[72:73] op_sel_hi:[1,0]
	v_add_f32_e32 v57, v68, v60
	v_min_f32_e32 v56, 0, v57
	v_mul_f32_e64 v57, |v57|, s57
	v_exp_f32_e32 v57, v57
	v_add_f32_e32 v61, v69, v61
	v_add_f32_e32 v73, v65, v73
	v_add_f32_e32 v57, 1.0, v57
	v_log_f32_e32 v57, v57
	s_nop 0
	v_mul_f32_e32 v60, 0x3f317217, v57
	v_fma_f32 v60, v57, s52, -v60
	v_fmac_f32_e32 v60, 0x3377d1cf, v57
	v_fmac_f32_e32 v60, 0x3f317217, v57
	v_mov_b32_e32 v62, v60
	v_add_f32_e32 v57, v64, v72
	v_min_f32_e32 v60, 0, v57
	v_mul_f32_e64 v57, |v57|, s57
	v_exp_f32_e32 v57, v57
	s_nop 0
	v_add_f32_e32 v57, 1.0, v57
	v_log_f32_e32 v57, v57
	s_nop 0
	v_mul_f32_e32 v63, 0x3f317217, v57
	v_fma_f32 v63, v57, s52, -v63
	v_fmac_f32_e32 v63, 0x3377d1cf, v57
	v_fmac_f32_e32 v63, 0x3f317217, v57
	v_mov_b32_e32 v72, v63
	v_min_f32_e32 v57, 0, v61
	v_mul_f32_e64 v61, |v61|, s57
	v_exp_f32_e32 v61, v61
	s_nop 0
	v_add_f32_e32 v61, 1.0, v61
	v_log_f32_e32 v61, v61
	s_nop 0
	v_mul_f32_e32 v63, 0x3f317217, v61
	v_fma_f32 v63, v61, s52, -v63
	v_fmac_f32_e32 v63, 0x3377d1cf, v61
	v_fmac_f32_e32 v63, 0x3f317217, v61
	v_mov_b32_e32 v63, v63
	v_min_f32_e32 v61, 0, v73
	v_mul_f32_e64 v73, |v73|, s57
	v_exp_f32_e32 v73, v73
	v_pk_add_f32 v[56:57], v[56:57], v[62:63] neg_lo:[0,1] neg_hi:[0,1]
	v_add_f32_e32 v73, 1.0, v73
	v_log_f32_e32 v73, v73
	s_nop 0
	v_mul_f32_e32 v76, 0x3f317217, v73
	v_fma_f32 v76, v73, s52, -v76
	v_fmac_f32_e32 v76, 0x3377d1cf, v73
	v_fmac_f32_e32 v76, 0x3f317217, v73
	v_mov_b32_e32 v73, v76
	v_add_f32_e32 v76, v70, v74
	v_min_f32_e32 v74, 0, v76
	v_mul_f32_e64 v76, |v76|, s57
	v_exp_f32_e32 v76, v76
	s_nop 0
	v_add_f32_e32 v76, 1.0, v76
	v_log_f32_e32 v76, v76
	s_nop 0
	v_mul_f32_e32 v77, 0x3f317217, v76
	v_fma_f32 v77, v76, s52, -v77
	v_fmac_f32_e32 v77, 0x3377d1cf, v76
	v_fmac_f32_e32 v77, 0x3f317217, v76
	v_mov_b32_e32 v76, v77
	v_add_f32_e32 v77, v66, v58
	v_min_f32_e32 v58, 0, v77
	v_mul_f32_e64 v77, |v77|, s57
	v_exp_f32_e32 v77, v77
	s_nop 0
	v_add_f32_e32 v77, 1.0, v77
	v_log_f32_e32 v77, v77
	s_nop 0
	v_mul_f32_e32 v78, 0x3f317217, v77
	v_fma_f32 v78, v77, s52, -v78
	v_fmac_f32_e32 v78, 0x3377d1cf, v77
	v_fmac_f32_e32 v78, 0x3f317217, v77
	v_mov_b32_e32 v78, v78
	v_add_f32_e32 v77, v71, v75
	v_min_f32_e32 v75, 0, v77
	v_mul_f32_e64 v77, |v77|, s57
	v_exp_f32_e32 v77, v77
	s_nop 0
	v_add_f32_e32 v77, 1.0, v77
	v_log_f32_e32 v77, v77
	s_nop 0
	v_mul_f32_e32 v79, 0x3f317217, v77
	v_fma_f32 v79, v77, s52, -v79
	v_fmac_f32_e32 v79, 0x3377d1cf, v77
	v_fmac_f32_e32 v79, 0x3f317217, v77
	v_mov_b32_e32 v77, v79
	v_pk_add_f32 v[62:63], v[74:75], v[76:77] neg_lo:[0,1] neg_hi:[0,1]
	v_pk_mul_f32 v[74:75], v[56:57], s[2:3] op_sel_hi:[1,0]
	v_add_f32_e32 v56, v67, v59
	v_min_f32_e32 v59, 0, v56
	v_mul_f32_e64 v56, |v56|, s57
	v_exp_f32_e32 v56, v56
	v_pk_mul_f32 v[76:77], v[62:63], s[2:3] op_sel_hi:[1,0]
	v_add_f32_e32 v56, 1.0, v56
	v_log_f32_e32 v56, v56
	s_nop 0
	v_mul_f32_e32 v57, 0x3f317217, v56
	v_fma_f32 v57, v56, s52, -v57
	v_fmac_f32_e32 v57, 0x3377d1cf, v56
	v_fmac_f32_e32 v57, 0x3f317217, v56
	v_mov_b32_e32 v79, v57
	v_pk_add_f32 v[56:57], v[60:61], v[72:73] neg_lo:[0,1] neg_hi:[0,1]
	v_lshlrev_b64 v[60:61], 5, v[166:167]
	v_pk_add_f32 v[58:59], v[58:59], v[78:79] neg_lo:[0,1] neg_hi:[0,1]
	v_pk_mul_f32 v[56:57], v[56:57], s[2:3] op_sel_hi:[1,0]
	v_lshl_add_u64 v[60:61], s[42:43], 0, v[60:61]
	v_pk_mul_f32 v[58:59], v[58:59], s[2:3] op_sel_hi:[1,0]
	global_store_dwordx4 v[60:61], v[74:77], off
	global_store_dwordx4 v[60:61], v[56:59], off offset:16
	s_nop 1
	v_or_b32_e32 v56, 16, v166
	v_ashrrev_i32_e32 v57, 31, v56
	v_lshlrev_b64 v[58:59], 6, v[56:57]
	v_lshl_add_u64 v[62:63], s[82:83], 0, v[58:59]
	s_waitcnt vmcnt(14)
; __device__ __forceinline__ float logsig_f(float x) { return fminf(x, 0.f) - __logf(1.f + __expf(-fabsf(x))); }
;     __device__ __forceinline__ void operator()(const f32x4 (&acc)[2][2][4][2], const pg8::Unit& u, int wr, int wc, int fr, int fq) const {
;     ...
;                     for (int m = 0; m < 4; ++m) {
;                         const int row = row0 + ai * 128 + m * 16;
;                         const f32x4 sv = *(const f32x4*)(ssq + (size_t)row * 16), sv1 = *(const f32x4*)(ssq + (size_t)row * 16 + 4), sv2 = *(const f32x4*)(ssq + (size_t)row * 16 + 8), sv3 = *(const f32x4*)(ssq + (size_t)row * 16 + 12);
;                         const float st = ((sv[0] + sv[1]) + (sv[2] + sv[3])) + ((sv1[0] + sv1[1]) + (sv1[2] + sv1[3])) + ((sv2[0] + sv2[1]) + (sv2[2] + sv2[3])) + ((sv3[0] + sv3[1]) + (sv3[2] + sv3[3]));
;                         const float rs = __builtin_amdgcn_rsqf(st * (1.f / DM) + EPS);
;                         f32x4 a = acc[ai][0][m][0] * rs, b = acc[ai][0][m][1] * rs;
; #pragma unroll
;                         for (int i = 0; i < 4; ++i) { a[i] = logsig_f(a[i] + fb0[i]) * LOG2E; b[i] = logsig_f(b[i] + fb1[i]) * LOG2E; }
;                         *(f32x4*)(FF + (size_t)row * 8) = a; *(f32x4*)(FF + (size_t)row * 8 + 4) = b;
;                         asm volatile("" ::: "memory");
	v_mov_b32_e32 v58, v144
	v_mov_b32_e32 v59, v145
	v_mov_b32_e32 v60, v146
	v_mov_b32_e32 v61, v147
	v_mov_b32_e32 v72, v148
	v_mov_b32_e32 v73, v149
	v_mov_b32_e32 v74, v150
	v_mov_b32_e32 v75, v151
	v_mov_b32_e32 v76, v168
	v_mov_b32_e32 v77, v169
	v_mov_b32_e32 v78, v170
	v_mov_b32_e32 v79, v171
	v_mov_b32_e32 v80, v176
	v_mov_b32_e32 v81, v177
	v_mov_b32_e32 v82, v178
	v_mov_b32_e32 v83, v179
	v_mov_b32_e32 v62, v59
	v_mov_b32_e32 v63, v60
	v_mov_b32_e32 v59, v61
	v_mov_b32_e32 v60, v73
	v_mov_b32_e32 v61, v74
	v_mov_b32_e32 v73, v75
	v_pk_add_f32 v[58:59], v[62:63], v[58:59]
	v_pk_add_f32 v[60:61], v[60:61], v[72:73]
	v_pk_add_f32 v[58:59], v[58:59], v[58:59] op_sel:[0,1] op_sel_hi:[1,0]
	v_pk_add_f32 v[60:61], v[60:61], v[60:61] op_sel:[0,1] op_sel_hi:[1,0]
	v_add_f32_e32 v62, v76, v77
	v_add_f32_e32 v72, v78, v79
	v_mov_b32_e32 v59, v80
	v_mov_b32_e32 v61, v81
	v_mov_b32_e32 v63, v82
	v_mov_b32_e32 v73, v83
	v_pk_add_f32 v[58:59], v[58:59], v[60:61]
	v_pk_add_f32 v[60:61], v[62:63], v[72:73]
	s_nop 0
	v_pk_add_f32 v[58:59], v[58:59], v[60:61]
	s_nop 0
	v_add_f32_e32 v58, v58, v59
	v_fmamk_f32 v58, v58, 0x3a800000, v212
	v_rsq_f32_e32 v60, v58
	global_load_dwordx4 v[144:147], v[220:221], off offset:1024
	global_load_dwordx4 v[148:151], v[220:221], off offset:1040
	global_load_dwordx4 v[168:171], v[220:221], off offset:1056
	global_load_dwordx4 v[176:179], v[220:221], off offset:1072
	v_pk_mul_f32 v[52:53], v[52:53], v[60:61] op_sel_hi:[1,0]
	v_pk_mul_f32 v[58:59], v[54:55], v[60:61] op_sel_hi:[1,0]
	v_add_f32_e32 v54, v68, v52
	v_min_f32_e32 v52, 0, v54
	v_mul_f32_e64 v54, |v54|, s57
	v_exp_f32_e32 v54, v54
	v_pk_mul_f32 v[48:49], v[48:49], v[60:61] op_sel_hi:[1,0]
	v_pk_mul_f32 v[50:51], v[50:51], v[60:61] op_sel_hi:[1,0]
	v_add_f32_e32 v54, 1.0, v54
	v_log_f32_e32 v54, v54
	s_nop 0
	v_mul_f32_e32 v55, 0x3f317217, v54
	v_fma_f32 v55, v54, s52, -v55
	v_fmac_f32_e32 v55, 0x3377d1cf, v54
	v_fmac_f32_e32 v55, 0x3f317217, v54
	v_mov_b32_e32 v60, v55
	v_add_f32_e32 v54, v64, v48
	v_min_f32_e32 v48, 0, v54
	v_mul_f32_e64 v54, |v54|, s57
	v_exp_f32_e32 v54, v54
	s_nop 0
	v_add_f32_e32 v54, 1.0, v54
	v_log_f32_e32 v54, v54
	s_nop 0
	v_mul_f32_e32 v55, 0x3f317217, v54
	v_fma_f32 v55, v54, s52, -v55
	v_fmac_f32_e32 v55, 0x3377d1cf, v54
	v_fmac_f32_e32 v55, 0x3f317217, v54
	v_mov_b32_e32 v54, v55
	v_add_f32_e32 v55, v69, v53
	v_min_f32_e32 v53, 0, v55
	v_mul_f32_e64 v55, |v55|, s57
	v_exp_f32_e32 v55, v55
	s_nop 0
	v_add_f32_e32 v55, 1.0, v55
	v_log_f32_e32 v55, v55
	s_nop 0
	v_mul_f32_e32 v61, 0x3f317217, v55
	v_fma_f32 v61, v55, s52, -v61
	v_fmac_f32_e32 v61, 0x3377d1cf, v55
	v_fmac_f32_e32 v61, 0x3f317217, v55
	v_mov_b32_e32 v61, v61
	v_add_f32_e32 v55, v65, v49
	v_min_f32_e32 v49, 0, v55
	v_mul_f32_e64 v55, |v55|, s57
	v_exp_f32_e32 v55, v55
	v_pk_add_f32 v[52:53], v[52:53], v[60:61] neg_lo:[0,1] neg_hi:[0,1]
	v_add_f32_e32 v55, 1.0, v55
	v_log_f32_e32 v55, v55
	s_nop 0
	v_mul_f32_e32 v62, 0x3f317217, v55
	v_fma_f32 v62, v55, s52, -v62
	v_fmac_f32_e32 v62, 0x3377d1cf, v55
	v_fmac_f32_e32 v62, 0x3f317217, v55
	v_mov_b32_e32 v55, v62
	v_add_f32_e32 v62, v70, v58
	v_min_f32_e32 v58, 0, v62
	v_mul_f32_e64 v62, |v62|, s57
	v_exp_f32_e32 v62, v62
	v_pk_add_f32 v[48:49], v[48:49], v[54:55] neg_lo:[0,1] neg_hi:[0,1]
	v_add_f32_e32 v62, 1.0, v62
	v_pk_mul_f32 v[48:49], v[48:49], s[2:3] op_sel_hi:[1,0]
	s_nop 0
	v_log_f32_e32 v62, v62
	s_nop 0
	v_mul_f32_e32 v63, 0x3f317217, v62
	v_fma_f32 v63, v62, s52, -v63
	v_fmac_f32_e32 v63, 0x3377d1cf, v62
	v_fmac_f32_e32 v63, 0x3f317217, v62
	v_mov_b32_e32 v62, v63
	v_add_f32_e32 v63, v66, v50
	v_min_f32_e32 v50, 0, v63
	v_mul_f32_e64 v63, |v63|, s57
	v_exp_f32_e32 v63, v63
	s_nop 0
	v_add_f32_e32 v63, 1.0, v63
	v_log_f32_e32 v63, v63
	s_nop 0
	v_mul_f32_e32 v72, 0x3f317217, v63
	v_fma_f32 v72, v63, s52, -v72
	v_fmac_f32_e32 v72, 0x3377d1cf, v63
	v_fmac_f32_e32 v72, 0x3f317217, v63
	v_mov_b32_e32 v72, v72
	v_add_f32_e32 v63, v71, v59
	v_min_f32_e32 v59, 0, v63
	v_mul_f32_e64 v63, |v63|, s57
	v_exp_f32_e32 v63, v63
	s_nop 0
	v_add_f32_e32 v63, 1.0, v63
	v_log_f32_e32 v63, v63
	s_nop 0
	v_mul_f32_e32 v73, 0x3f317217, v63
	v_fma_f32 v73, v63, s52, -v73
	v_fmac_f32_e32 v73, 0x3377d1cf, v63
	v_fmac_f32_e32 v73, 0x3f317217, v63
	v_mov_b32_e32 v63, v73
	v_pk_add_f32 v[58:59], v[58:59], v[62:63] neg_lo:[0,1] neg_hi:[0,1]
	s_nop 0
	v_pk_mul_f32 v[60:61], v[58:59], s[2:3] op_sel_hi:[1,0]
	v_pk_mul_f32 v[58:59], v[52:53], s[2:3] op_sel_hi:[1,0]
	v_add_f32_e32 v52, v67, v51
	v_min_f32_e32 v51, 0, v52
	v_mul_f32_e64 v52, |v52|, s57
	v_exp_f32_e32 v52, v52
	s_nop 0
	v_add_f32_e32 v52, 1.0, v52
	v_log_f32_e32 v52, v52
	s_nop 0
	v_mul_f32_e32 v53, 0x3f317217, v52
	v_fma_f32 v53, v52, s52, -v53
	v_fmac_f32_e32 v53, 0x3377d1cf, v52
	v_fmac_f32_e32 v53, 0x3f317217, v52
	v_mov_b32_e32 v73, v53
	v_lshlrev_b64 v[52:53], 5, v[56:57]
	v_pk_add_f32 v[50:51], v[50:51], v[72:73] neg_lo:[0,1] neg_hi:[0,1]
	v_lshl_add_u64 v[52:53], s[42:43], 0, v[52:53]
	v_pk_mul_f32 v[50:51], v[50:51], s[2:3] op_sel_hi:[1,0]
	global_store_dwordx4 v[52:53], v[58:61], off
	global_store_dwordx4 v[52:53], v[48:51], off offset:16
	s_nop 1
	v_or_b32_e32 v48, 32, v166
	v_ashrrev_i32_e32 v49, 31, v48
	v_lshlrev_b64 v[50:51], 6, v[48:49]
	v_lshl_add_u64 v[62:63], s[82:83], 0, v[50:51]
	s_waitcnt vmcnt(16)
; __device__ __forceinline__ float logsig_f(float x) { return fminf(x, 0.f) - __logf(1.f + __expf(-fabsf(x))); }
;     __device__ __forceinline__ void operator()(const f32x4 (&acc)[2][2][4][2], const pg8::Unit& u, int wr, int wc, int fr, int fq) const {
;     ...
;                     for (int m = 0; m < 4; ++m) {
;                         const int row = row0 + ai * 128 + m * 16;
;                         const f32x4 sv = *(const f32x4*)(ssq + (size_t)row * 16), sv1 = *(const f32x4*)(ssq + (size_t)row * 16 + 4), sv2 = *(const f32x4*)(ssq + (size_t)row * 16 + 8), sv3 = *(const f32x4*)(ssq + (size_t)row * 16 + 12);
;                         const float st = ((sv[0] + sv[1]) + (sv[2] + sv[3])) + ((sv1[0] + sv1[1]) + (sv1[2] + sv1[3])) + ((sv2[0] + sv2[1]) + (sv2[2] + sv2[3])) + ((sv3[0] + sv3[1]) + (sv3[2] + sv3[3]));
;                         const float rs = __builtin_amdgcn_rsqf(st * (1.f / DM) + EPS);
;                         f32x4 a = acc[ai][0][m][0] * rs, b = acc[ai][0][m][1] * rs;
; #pragma unroll
;                         for (int i = 0; i < 4; ++i) { a[i] = logsig_f(a[i] + fb0[i]) * LOG2E; b[i] = logsig_f(b[i] + fb1[i]) * LOG2E; }
;                         *(f32x4*)(FF + (size_t)row * 8) = a; *(f32x4*)(FF + (size_t)row * 8 + 4) = b;
;                         asm volatile("" ::: "memory");
	v_mov_b32_e32 v50, v180
	v_mov_b32_e32 v51, v181
	v_mov_b32_e32 v52, v182
	v_mov_b32_e32 v53, v183
	v_mov_b32_e32 v54, v184
	v_mov_b32_e32 v55, v185
	v_mov_b32_e32 v56, v186
	v_mov_b32_e32 v57, v187
	v_mov_b32_e32 v58, v188
	v_mov_b32_e32 v59, v189
	v_mov_b32_e32 v60, v190
	v_mov_b32_e32 v61, v191
	v_mov_b32_e32 v72, v204
	v_mov_b32_e32 v73, v205
	v_mov_b32_e32 v74, v206
	v_mov_b32_e32 v75, v207
	v_mov_b32_e32 v62, v51
	v_mov_b32_e32 v63, v52
	v_mov_b32_e32 v51, v53
	v_mov_b32_e32 v52, v55
	v_mov_b32_e32 v53, v56
	v_mov_b32_e32 v55, v57
	v_pk_add_f32 v[50:51], v[62:63], v[50:51]
	v_pk_add_f32 v[52:53], v[52:53], v[54:55]
	v_pk_add_f32 v[50:51], v[50:51], v[50:51] op_sel:[0,1] op_sel_hi:[1,0]
	v_pk_add_f32 v[52:53], v[52:53], v[52:53] op_sel:[0,1] op_sel_hi:[1,0]
	v_add_f32_e32 v54, v58, v59
	v_add_f32_e32 v56, v60, v61
	v_mov_b32_e32 v51, v72
	v_mov_b32_e32 v53, v73
	v_mov_b32_e32 v55, v74
	v_mov_b32_e32 v57, v75
	v_pk_add_f32 v[50:51], v[50:51], v[52:53]
	v_pk_add_f32 v[52:53], v[54:55], v[56:57]
	s_nop 0
	v_pk_add_f32 v[50:51], v[50:51], v[52:53]
	s_nop 0
	v_add_f32_e32 v50, v50, v51
	v_fmamk_f32 v50, v50, 0x3a800000, v212
	v_rsq_f32_e32 v52, v50
	global_load_dwordx4 v[180:183], v[220:221], off offset:2048
	global_load_dwordx4 v[184:187], v[220:221], off offset:2064
	global_load_dwordx4 v[188:191], v[220:221], off offset:2080
	global_load_dwordx4 v[204:207], v[220:221], off offset:2096
	v_pk_mul_f32 v[44:45], v[44:45], v[52:53] op_sel_hi:[1,0]
	v_pk_mul_f32 v[50:51], v[46:47], v[52:53] op_sel_hi:[1,0]
	v_add_f32_e32 v46, v68, v44
	v_min_f32_e32 v44, 0, v46
	v_mul_f32_e64 v46, |v46|, s57
	v_exp_f32_e32 v46, v46
	v_pk_mul_f32 v[40:41], v[40:41], v[52:53] op_sel_hi:[1,0]
	v_pk_mul_f32 v[42:43], v[42:43], v[52:53] op_sel_hi:[1,0]
	v_add_f32_e32 v46, 1.0, v46
	v_log_f32_e32 v46, v46
	s_nop 0
	v_mul_f32_e32 v47, 0x3f317217, v46
	v_fma_f32 v47, v46, s52, -v47
	v_fmac_f32_e32 v47, 0x3377d1cf, v46
	v_fmac_f32_e32 v47, 0x3f317217, v46
	v_mov_b32_e32 v52, v47
	v_add_f32_e32 v46, v64, v40
	v_min_f32_e32 v40, 0, v46
	v_mul_f32_e64 v46, |v46|, s57
	v_exp_f32_e32 v46, v46
	s_nop 0
	v_add_f32_e32 v46, 1.0, v46
	v_log_f32_e32 v46, v46
	s_nop 0
	v_mul_f32_e32 v47, 0x3f317217, v46
	v_fma_f32 v47, v46, s52, -v47
	v_fmac_f32_e32 v47, 0x3377d1cf, v46
	v_fmac_f32_e32 v47, 0x3f317217, v46
	v_mov_b32_e32 v46, v47
	v_add_f32_e32 v47, v69, v45
	v_min_f32_e32 v45, 0, v47
	v_mul_f32_e64 v47, |v47|, s57
	v_exp_f32_e32 v47, v47
	s_nop 0
	v_add_f32_e32 v47, 1.0, v47
	v_log_f32_e32 v47, v47
	s_nop 0
	v_mul_f32_e32 v53, 0x3f317217, v47
	v_fma_f32 v53, v47, s52, -v53
	v_fmac_f32_e32 v53, 0x3377d1cf, v47
	v_fmac_f32_e32 v53, 0x3f317217, v47
	v_mov_b32_e32 v53, v53
	v_add_f32_e32 v47, v65, v41
	v_min_f32_e32 v41, 0, v47
	v_mul_f32_e64 v47, |v47|, s57
	v_exp_f32_e32 v47, v47
	v_pk_add_f32 v[44:45], v[44:45], v[52:53] neg_lo:[0,1] neg_hi:[0,1]
	v_add_f32_e32 v47, 1.0, v47
	v_log_f32_e32 v47, v47
	s_nop 0
	v_mul_f32_e32 v54, 0x3f317217, v47
	v_fma_f32 v54, v47, s52, -v54
	v_fmac_f32_e32 v54, 0x3377d1cf, v47
	v_fmac_f32_e32 v54, 0x3f317217, v47
	v_mov_b32_e32 v47, v54
	v_add_f32_e32 v54, v70, v50
	v_min_f32_e32 v50, 0, v54
	v_mul_f32_e64 v54, |v54|, s57
	v_exp_f32_e32 v54, v54
	v_pk_add_f32 v[40:41], v[40:41], v[46:47] neg_lo:[0,1] neg_hi:[0,1]
	v_add_f32_e32 v54, 1.0, v54
	v_pk_mul_f32 v[40:41], v[40:41], s[2:3] op_sel_hi:[1,0]
	s_nop 0
	v_log_f32_e32 v54, v54
	s_nop 0
	v_mul_f32_e32 v55, 0x3f317217, v54
	v_fma_f32 v55, v54, s52, -v55
	v_fmac_f32_e32 v55, 0x3377d1cf, v54
	v_fmac_f32_e32 v55, 0x3f317217, v54
	v_mov_b32_e32 v54, v55
	v_add_f32_e32 v55, v66, v42
	v_min_f32_e32 v42, 0, v55
	v_mul_f32_e64 v55, |v55|, s57
	v_exp_f32_e32 v55, v55
	s_nop 0
	v_add_f32_e32 v55, 1.0, v55
	v_log_f32_e32 v55, v55
	s_nop 0
	v_mul_f32_e32 v56, 0x3f317217, v55
	v_fma_f32 v56, v55, s52, -v56
	v_fmac_f32_e32 v56, 0x3377d1cf, v55
	v_fmac_f32_e32 v56, 0x3f317217, v55
	v_mov_b32_e32 v56, v56
	v_add_f32_e32 v55, v71, v51
	v_min_f32_e32 v51, 0, v55
	v_mul_f32_e64 v55, |v55|, s57
	v_exp_f32_e32 v55, v55
	s_nop 0
	v_add_f32_e32 v55, 1.0, v55
	v_log_f32_e32 v55, v55
	s_nop 0
	v_mul_f32_e32 v57, 0x3f317217, v55
	v_fma_f32 v57, v55, s52, -v57
	v_fmac_f32_e32 v57, 0x3377d1cf, v55
	v_fmac_f32_e32 v57, 0x3f317217, v55
	v_mov_b32_e32 v55, v57
	v_pk_add_f32 v[50:51], v[50:51], v[54:55] neg_lo:[0,1] neg_hi:[0,1]
	s_nop 0
	v_pk_mul_f32 v[52:53], v[50:51], s[2:3] op_sel_hi:[1,0]
	v_pk_mul_f32 v[50:51], v[44:45], s[2:3] op_sel_hi:[1,0]
	v_add_f32_e32 v44, v67, v43
	v_min_f32_e32 v43, 0, v44
	v_mul_f32_e64 v44, |v44|, s57
	v_exp_f32_e32 v44, v44
	s_nop 0
	v_add_f32_e32 v44, 1.0, v44
	v_log_f32_e32 v44, v44
	s_nop 0
	v_mul_f32_e32 v45, 0x3f317217, v44
	v_fma_f32 v45, v44, s52, -v45
	v_fmac_f32_e32 v45, 0x3377d1cf, v44
	v_fmac_f32_e32 v45, 0x3f317217, v44
	v_mov_b32_e32 v57, v45
	v_lshlrev_b64 v[44:45], 5, v[48:49]
	v_pk_add_f32 v[42:43], v[42:43], v[56:57] neg_lo:[0,1] neg_hi:[0,1]
	v_lshl_add_u64 v[44:45], s[42:43], 0, v[44:45]
	v_pk_mul_f32 v[42:43], v[42:43], s[2:3] op_sel_hi:[1,0]
	global_store_dwordx4 v[44:45], v[50:53], off
	global_store_dwordx4 v[44:45], v[40:43], off offset:16
	s_nop 1
	v_or_b32_e32 v40, 48, v166
	v_ashrrev_i32_e32 v41, 31, v40
	v_lshlrev_b64 v[42:43], 6, v[40:41]
	v_lshl_add_u64 v[54:55], s[82:83], 0, v[42:43]
	s_nop 0
	s_waitcnt vmcnt(18)
; __device__ __forceinline__ float logsig_f(float x) { return fminf(x, 0.f) - __logf(1.f + __expf(-fabsf(x))); }
;     __device__ __forceinline__ void operator()(const f32x4 (&acc)[2][2][4][2], const pg8::Unit& u, int wr, int wc, int fr, int fq) const {
;     ...
;                     for (int m = 0; m < 4; ++m) {
;                         const int row = row0 + ai * 128 + m * 16;
;                         const f32x4 sv = *(const f32x4*)(ssq + (size_t)row * 16), sv1 = *(const f32x4*)(ssq + (size_t)row * 16 + 4), sv2 = *(const f32x4*)(ssq + (size_t)row * 16 + 8), sv3 = *(const f32x4*)(ssq + (size_t)row * 16 + 12);
;                         const float st = ((sv[0] + sv[1]) + (sv[2] + sv[3])) + ((sv1[0] + sv1[1]) + (sv1[2] + sv1[3])) + ((sv2[0] + sv2[1]) + (sv2[2] + sv2[3])) + ((sv3[0] + sv3[1]) + (sv3[2] + sv3[3]));
;                         const float rs = __builtin_amdgcn_rsqf(st * (1.f / DM) + EPS);
;                         f32x4 a = acc[ai][0][m][0] * rs, b = acc[ai][0][m][1] * rs;
; #pragma unroll
;                         for (int i = 0; i < 4; ++i) { a[i] = logsig_f(a[i] + fb0[i]) * LOG2E; b[i] = logsig_f(b[i] + fb1[i]) * LOG2E; }
;                         *(f32x4*)(FF + (size_t)row * 8) = a; *(f32x4*)(FF + (size_t)row * 8 + 4) = b;
;                         asm volatile("" ::: "memory");
	v_mov_b32_e32 v42, v208
	v_mov_b32_e32 v43, v209
	v_mov_b32_e32 v44, v210
	v_mov_b32_e32 v45, v211
	v_mov_b32_e32 v46, v224
	v_mov_b32_e32 v47, v225
	v_mov_b32_e32 v48, v226
	v_mov_b32_e32 v49, v227
	v_mov_b32_e32 v50, v228
	v_mov_b32_e32 v51, v229
	v_mov_b32_e32 v52, v230
	v_mov_b32_e32 v53, v231
	v_mov_b32_e32 v54, v232
	v_mov_b32_e32 v55, v233
	v_mov_b32_e32 v56, v234
	v_mov_b32_e32 v57, v235
	v_mov_b32_e32 v58, v43
	v_mov_b32_e32 v59, v44
	v_mov_b32_e32 v43, v45
	v_mov_b32_e32 v44, v47
	v_mov_b32_e32 v45, v48
	v_mov_b32_e32 v47, v49
	v_pk_add_f32 v[42:43], v[58:59], v[42:43]
	v_pk_add_f32 v[44:45], v[44:45], v[46:47]
	v_pk_add_f32 v[42:43], v[42:43], v[42:43] op_sel:[0,1] op_sel_hi:[1,0]
	v_pk_add_f32 v[44:45], v[44:45], v[44:45] op_sel:[0,1] op_sel_hi:[1,0]
	v_add_f32_e32 v46, v50, v51
	v_add_f32_e32 v48, v52, v53
	v_mov_b32_e32 v43, v54
	v_mov_b32_e32 v45, v55
	v_mov_b32_e32 v47, v56
	v_mov_b32_e32 v49, v57
	v_pk_add_f32 v[42:43], v[42:43], v[44:45]
	v_pk_add_f32 v[44:45], v[46:47], v[48:49]
	s_nop 0
	v_pk_add_f32 v[42:43], v[42:43], v[44:45]
	s_nop 0
	v_add_f32_e32 v42, v42, v43
	v_fmamk_f32 v42, v42, 0x3a800000, v212
	v_rsq_f32_e32 v44, v42
	global_load_dwordx4 v[208:211], v[220:221], off offset:3072
	global_load_dwordx4 v[224:227], v[220:221], off offset:3088
	global_load_dwordx4 v[228:231], v[220:221], off offset:3104
	global_load_dwordx4 v[232:235], v[220:221], off offset:3120
	v_pk_mul_f32 v[36:37], v[36:37], v[44:45] op_sel_hi:[1,0]
	v_pk_mul_f32 v[42:43], v[38:39], v[44:45] op_sel_hi:[1,0]
	v_add_f32_e32 v38, v68, v36
	v_min_f32_e32 v36, 0, v38
	v_mul_f32_e64 v38, |v38|, s57
	v_exp_f32_e32 v38, v38
	v_pk_mul_f32 v[32:33], v[32:33], v[44:45] op_sel_hi:[1,0]
	v_pk_mul_f32 v[34:35], v[34:35], v[44:45] op_sel_hi:[1,0]
	v_add_f32_e32 v38, 1.0, v38
	v_log_f32_e32 v38, v38
	s_nop 0
	v_mul_f32_e32 v39, 0x3f317217, v38
	v_fma_f32 v39, v38, s52, -v39
	v_fmac_f32_e32 v39, 0x3377d1cf, v38
	v_fmac_f32_e32 v39, 0x3f317217, v38
	v_mov_b32_e32 v44, v39
	v_add_f32_e32 v38, v64, v32
	v_min_f32_e32 v32, 0, v38
	v_mul_f32_e64 v38, |v38|, s57
	v_exp_f32_e32 v38, v38
	s_nop 0
	v_add_f32_e32 v38, 1.0, v38
	v_log_f32_e32 v38, v38
	s_nop 0
	v_mul_f32_e32 v39, 0x3f317217, v38
	v_fma_f32 v39, v38, s52, -v39
	v_fmac_f32_e32 v39, 0x3377d1cf, v38
	v_fmac_f32_e32 v39, 0x3f317217, v38
	v_mov_b32_e32 v38, v39
	v_add_f32_e32 v39, v69, v37
	v_min_f32_e32 v37, 0, v39
	v_mul_f32_e64 v39, |v39|, s57
	v_exp_f32_e32 v39, v39
	s_nop 0
	v_add_f32_e32 v39, 1.0, v39
	v_log_f32_e32 v39, v39
	s_nop 0
	v_mul_f32_e32 v45, 0x3f317217, v39
	v_fma_f32 v45, v39, s52, -v45
	v_fmac_f32_e32 v45, 0x3377d1cf, v39
	v_fmac_f32_e32 v45, 0x3f317217, v39
	v_mov_b32_e32 v45, v45
	v_add_f32_e32 v39, v65, v33
	v_min_f32_e32 v33, 0, v39
	v_mul_f32_e64 v39, |v39|, s57
	v_exp_f32_e32 v39, v39
	v_pk_add_f32 v[36:37], v[36:37], v[44:45] neg_lo:[0,1] neg_hi:[0,1]
	v_add_f32_e32 v39, 1.0, v39
	v_log_f32_e32 v39, v39
	s_nop 0
	v_mul_f32_e32 v46, 0x3f317217, v39
	v_fma_f32 v46, v39, s52, -v46
	v_fmac_f32_e32 v46, 0x3377d1cf, v39
	v_fmac_f32_e32 v46, 0x3f317217, v39
	v_mov_b32_e32 v39, v46
	v_add_f32_e32 v46, v70, v42
	v_min_f32_e32 v42, 0, v46
	v_mul_f32_e64 v46, |v46|, s57
	v_exp_f32_e32 v46, v46
	v_pk_add_f32 v[32:33], v[32:33], v[38:39] neg_lo:[0,1] neg_hi:[0,1]
	v_add_f32_e32 v46, 1.0, v46
	v_pk_mul_f32 v[32:33], v[32:33], s[2:3] op_sel_hi:[1,0]
	s_nop 0
	v_log_f32_e32 v46, v46
	s_nop 0
	v_mul_f32_e32 v47, 0x3f317217, v46
	v_fma_f32 v47, v46, s52, -v47
	v_fmac_f32_e32 v47, 0x3377d1cf, v46
	v_fmac_f32_e32 v47, 0x3f317217, v46
	v_mov_b32_e32 v46, v47
	v_add_f32_e32 v47, v66, v34
	v_min_f32_e32 v34, 0, v47
	v_mul_f32_e64 v47, |v47|, s57
	v_exp_f32_e32 v47, v47
	s_nop 0
	v_add_f32_e32 v47, 1.0, v47
	v_log_f32_e32 v47, v47
	s_nop 0
	v_mul_f32_e32 v48, 0x3f317217, v47
	v_fma_f32 v48, v47, s52, -v48
	v_fmac_f32_e32 v48, 0x3377d1cf, v47
	v_fmac_f32_e32 v48, 0x3f317217, v47
	v_mov_b32_e32 v48, v48
	v_add_f32_e32 v47, v71, v43
	v_min_f32_e32 v43, 0, v47
	v_mul_f32_e64 v47, |v47|, s57
	v_exp_f32_e32 v47, v47
	s_nop 0
	v_add_f32_e32 v47, 1.0, v47
	v_log_f32_e32 v47, v47
	s_nop 0
	v_mul_f32_e32 v49, 0x3f317217, v47
	v_fma_f32 v49, v47, s52, -v49
	v_fmac_f32_e32 v49, 0x3377d1cf, v47
	v_fmac_f32_e32 v49, 0x3f317217, v47
	v_mov_b32_e32 v47, v49
	v_pk_add_f32 v[42:43], v[42:43], v[46:47] neg_lo:[0,1] neg_hi:[0,1]
	s_nop 0
	v_pk_mul_f32 v[44:45], v[42:43], s[2:3] op_sel_hi:[1,0]
	v_pk_mul_f32 v[42:43], v[36:37], s[2:3] op_sel_hi:[1,0]
	v_add_f32_e32 v36, v67, v35
	v_min_f32_e32 v35, 0, v36
	v_mul_f32_e64 v36, |v36|, s57
	v_exp_f32_e32 v36, v36
	s_nop 0
	v_add_f32_e32 v36, 1.0, v36
	v_log_f32_e32 v36, v36
	s_nop 0
	v_mul_f32_e32 v37, 0x3f317217, v36
	v_fma_f32 v37, v36, s52, -v37
	v_fmac_f32_e32 v37, 0x3377d1cf, v36
	v_fmac_f32_e32 v37, 0x3f317217, v36
	v_mov_b32_e32 v49, v37
	v_lshlrev_b64 v[36:37], 5, v[40:41]
	v_pk_add_f32 v[34:35], v[34:35], v[48:49] neg_lo:[0,1] neg_hi:[0,1]
	v_lshl_add_u64 v[36:37], s[42:43], 0, v[36:37]
	v_pk_mul_f32 v[34:35], v[34:35], s[2:3] op_sel_hi:[1,0]
	global_store_dwordx4 v[36:37], v[42:45], off
	global_store_dwordx4 v[36:37], v[32:35], off offset:16
	s_nop 1
	v_add_u32_e32 v32, 0x80, v166
	v_ashrrev_i32_e32 v33, 31, v32
	v_lshlrev_b64 v[34:35], 6, v[32:33]
	v_lshl_add_u64 v[46:47], s[82:83], 0, v[34:35]
	s_nop 0
	s_waitcnt vmcnt(20)
; __device__ __forceinline__ float logsig_f(float x) { return fminf(x, 0.f) - __logf(1.f + __expf(-fabsf(x))); }
;     __device__ __forceinline__ void operator()(const f32x4 (&acc)[2][2][4][2], const pg8::Unit& u, int wr, int wc, int fr, int fq) const {
;     ...
;                     for (int m = 0; m < 4; ++m) {
;                         const int row = row0 + ai * 128 + m * 16;
;                         const f32x4 sv = *(const f32x4*)(ssq + (size_t)row * 16), sv1 = *(const f32x4*)(ssq + (size_t)row * 16 + 4), sv2 = *(const f32x4*)(ssq + (size_t)row * 16 + 8), sv3 = *(const f32x4*)(ssq + (size_t)row * 16 + 12);
;                         const float st = ((sv[0] + sv[1]) + (sv[2] + sv[3])) + ((sv1[0] + sv1[1]) + (sv1[2] + sv1[3])) + ((sv2[0] + sv2[1]) + (sv2[2] + sv2[3])) + ((sv3[0] + sv3[1]) + (sv3[2] + sv3[3]));
;                         const float rs = __builtin_amdgcn_rsqf(st * (1.f / DM) + EPS);
;                         f32x4 a = acc[ai][0][m][0] * rs, b = acc[ai][0][m][1] * rs;
; #pragma unroll
;                         for (int i = 0; i < 4; ++i) { a[i] = logsig_f(a[i] + fb0[i]) * LOG2E; b[i] = logsig_f(b[i] + fb1[i]) * LOG2E; }
;                         *(f32x4*)(FF + (size_t)row * 8) = a; *(f32x4*)(FF + (size_t)row * 8 + 4) = b;
;                         asm volatile("" ::: "memory");
	v_mov_b32_e32 v34, v128
	v_mov_b32_e32 v35, v129
	v_mov_b32_e32 v36, v130
	v_mov_b32_e32 v37, v131
	v_mov_b32_e32 v38, v132
	v_mov_b32_e32 v39, v133
	v_mov_b32_e32 v40, v134
	v_mov_b32_e32 v41, v135
	v_mov_b32_e32 v42, v136
	v_mov_b32_e32 v43, v137
	v_mov_b32_e32 v44, v138
	v_mov_b32_e32 v45, v139
	v_mov_b32_e32 v46, v140
	v_mov_b32_e32 v47, v141
	v_mov_b32_e32 v48, v142
	v_mov_b32_e32 v49, v143
	v_mov_b32_e32 v50, v35
	v_mov_b32_e32 v51, v36
	v_mov_b32_e32 v35, v37
	v_mov_b32_e32 v36, v39
	v_mov_b32_e32 v37, v40
	v_mov_b32_e32 v39, v41
	v_pk_add_f32 v[34:35], v[50:51], v[34:35]
	v_pk_add_f32 v[36:37], v[36:37], v[38:39]
	v_pk_add_f32 v[34:35], v[34:35], v[34:35] op_sel:[0,1] op_sel_hi:[1,0]
	v_pk_add_f32 v[36:37], v[36:37], v[36:37] op_sel:[0,1] op_sel_hi:[1,0]
	v_add_f32_e32 v38, v42, v43
	v_add_f32_e32 v40, v44, v45
	v_mov_b32_e32 v35, v46
	v_mov_b32_e32 v37, v47
	v_mov_b32_e32 v39, v48
	v_mov_b32_e32 v41, v49
	v_pk_add_f32 v[34:35], v[34:35], v[36:37]
	v_pk_add_f32 v[36:37], v[38:39], v[40:41]
	s_nop 0
	v_pk_add_f32 v[34:35], v[34:35], v[36:37]
	s_nop 0
	v_add_f32_e32 v34, v34, v35
	v_fmamk_f32 v34, v34, 0x3a800000, v212
	v_rsq_f32_e32 v36, v34
	s_nop 0
	v_pk_mul_f32 v[28:29], v[28:29], v[36:37] op_sel_hi:[1,0]
	v_pk_mul_f32 v[34:35], v[30:31], v[36:37] op_sel_hi:[1,0]
	v_add_f32_e32 v30, v68, v28
	v_min_f32_e32 v28, 0, v30
	v_mul_f32_e64 v30, |v30|, s57
	v_exp_f32_e32 v30, v30
	v_pk_mul_f32 v[24:25], v[24:25], v[36:37] op_sel_hi:[1,0]
	v_pk_mul_f32 v[26:27], v[26:27], v[36:37] op_sel_hi:[1,0]
	v_add_f32_e32 v30, 1.0, v30
	v_log_f32_e32 v30, v30
	s_nop 0
	v_mul_f32_e32 v31, 0x3f317217, v30
	v_fma_f32 v31, v30, s52, -v31
	v_fmac_f32_e32 v31, 0x3377d1cf, v30
	v_fmac_f32_e32 v31, 0x3f317217, v30
	v_mov_b32_e32 v36, v31
	v_add_f32_e32 v30, v64, v24
	v_min_f32_e32 v24, 0, v30
	v_mul_f32_e64 v30, |v30|, s57
	v_exp_f32_e32 v30, v30
	s_nop 0
	v_add_f32_e32 v30, 1.0, v30
	v_log_f32_e32 v30, v30
	s_nop 0
	v_mul_f32_e32 v31, 0x3f317217, v30
	v_fma_f32 v31, v30, s52, -v31
	v_fmac_f32_e32 v31, 0x3377d1cf, v30
	v_fmac_f32_e32 v31, 0x3f317217, v30
	v_mov_b32_e32 v30, v31
	v_add_f32_e32 v31, v69, v29
	v_min_f32_e32 v29, 0, v31
	v_mul_f32_e64 v31, |v31|, s57
	v_exp_f32_e32 v31, v31
	s_nop 0
	v_add_f32_e32 v31, 1.0, v31
	v_log_f32_e32 v31, v31
	s_nop 0
	v_mul_f32_e32 v37, 0x3f317217, v31
	v_fma_f32 v37, v31, s52, -v37
	v_fmac_f32_e32 v37, 0x3377d1cf, v31
	v_fmac_f32_e32 v37, 0x3f317217, v31
	v_mov_b32_e32 v37, v37
	v_add_f32_e32 v31, v65, v25
	v_min_f32_e32 v25, 0, v31
	v_mul_f32_e64 v31, |v31|, s57
	v_exp_f32_e32 v31, v31
	v_pk_add_f32 v[28:29], v[28:29], v[36:37] neg_lo:[0,1] neg_hi:[0,1]
	v_add_f32_e32 v31, 1.0, v31
	v_log_f32_e32 v31, v31
	s_nop 0
	v_mul_f32_e32 v38, 0x3f317217, v31
	v_fma_f32 v38, v31, s52, -v38
	v_fmac_f32_e32 v38, 0x3377d1cf, v31
	v_fmac_f32_e32 v38, 0x3f317217, v31
	v_mov_b32_e32 v31, v38
	v_add_f32_e32 v38, v70, v34
	v_min_f32_e32 v34, 0, v38
	v_mul_f32_e64 v38, |v38|, s57
	v_exp_f32_e32 v38, v38
	v_pk_add_f32 v[24:25], v[24:25], v[30:31] neg_lo:[0,1] neg_hi:[0,1]
	v_add_f32_e32 v38, 1.0, v38
	v_pk_mul_f32 v[24:25], v[24:25], s[2:3] op_sel_hi:[1,0]
	s_nop 0
	v_log_f32_e32 v38, v38
	s_nop 0
	v_mul_f32_e32 v39, 0x3f317217, v38
	v_fma_f32 v39, v38, s52, -v39
	v_fmac_f32_e32 v39, 0x3377d1cf, v38
	v_fmac_f32_e32 v39, 0x3f317217, v38
	v_mov_b32_e32 v38, v39
	v_add_f32_e32 v39, v66, v26
	v_min_f32_e32 v26, 0, v39
	v_mul_f32_e64 v39, |v39|, s57
	v_exp_f32_e32 v39, v39
	s_nop 0
	v_add_f32_e32 v39, 1.0, v39
	v_log_f32_e32 v39, v39
	s_nop 0
	v_mul_f32_e32 v40, 0x3f317217, v39
	v_fma_f32 v40, v39, s52, -v40
	v_fmac_f32_e32 v40, 0x3377d1cf, v39
	v_fmac_f32_e32 v40, 0x3f317217, v39
	v_mov_b32_e32 v40, v40
	v_add_f32_e32 v39, v71, v35
	v_min_f32_e32 v35, 0, v39
	v_mul_f32_e64 v39, |v39|, s57
	v_exp_f32_e32 v39, v39
	s_nop 0
	v_add_f32_e32 v39, 1.0, v39
	v_log_f32_e32 v39, v39
	s_nop 0
	v_mul_f32_e32 v41, 0x3f317217, v39
	v_fma_f32 v41, v39, s52, -v41
	v_fmac_f32_e32 v41, 0x3377d1cf, v39
	v_fmac_f32_e32 v41, 0x3f317217, v39
	v_mov_b32_e32 v39, v41
	v_pk_add_f32 v[34:35], v[34:35], v[38:39] neg_lo:[0,1] neg_hi:[0,1]
	s_nop 0
	v_pk_mul_f32 v[36:37], v[34:35], s[2:3] op_sel_hi:[1,0]
	v_pk_mul_f32 v[34:35], v[28:29], s[2:3] op_sel_hi:[1,0]
	v_add_f32_e32 v28, v67, v27
	v_min_f32_e32 v27, 0, v28
	v_mul_f32_e64 v28, |v28|, s57
	v_exp_f32_e32 v28, v28
	s_nop 0
	v_add_f32_e32 v28, 1.0, v28
	v_log_f32_e32 v28, v28
	s_nop 0
	v_mul_f32_e32 v29, 0x3f317217, v28
	v_fma_f32 v29, v28, s52, -v29
	v_fmac_f32_e32 v29, 0x3377d1cf, v28
	v_fmac_f32_e32 v29, 0x3f317217, v28
	v_mov_b32_e32 v41, v29
	v_lshlrev_b64 v[28:29], 5, v[32:33]
	v_pk_add_f32 v[26:27], v[26:27], v[40:41] neg_lo:[0,1] neg_hi:[0,1]
	v_lshl_add_u64 v[28:29], s[42:43], 0, v[28:29]
	v_pk_mul_f32 v[26:27], v[26:27], s[2:3] op_sel_hi:[1,0]
	global_store_dwordx4 v[28:29], v[34:37], off
	global_store_dwordx4 v[28:29], v[24:27], off offset:16
	s_nop 1
	v_add_u32_e32 v24, 0x90, v166
	v_ashrrev_i32_e32 v25, 31, v24
	v_lshlrev_b64 v[26:27], 6, v[24:25]
	v_lshl_add_u64 v[38:39], s[82:83], 0, v[26:27]
	s_nop 0
	s_waitcnt vmcnt(16)
; __device__ __forceinline__ float logsig_f(float x) { return fminf(x, 0.f) - __logf(1.f + __expf(-fabsf(x))); }
;     __device__ __forceinline__ void operator()(const f32x4 (&acc)[2][2][4][2], const pg8::Unit& u, int wr, int wc, int fr, int fq) const {
;     ...
;                     for (int m = 0; m < 4; ++m) {
;                         const int row = row0 + ai * 128 + m * 16;
;                         const f32x4 sv = *(const f32x4*)(ssq + (size_t)row * 16), sv1 = *(const f32x4*)(ssq + (size_t)row * 16 + 4), sv2 = *(const f32x4*)(ssq + (size_t)row * 16 + 8), sv3 = *(const f32x4*)(ssq + (size_t)row * 16 + 12);
;                         const float st = ((sv[0] + sv[1]) + (sv[2] + sv[3])) + ((sv1[0] + sv1[1]) + (sv1[2] + sv1[3])) + ((sv2[0] + sv2[1]) + (sv2[2] + sv2[3])) + ((sv3[0] + sv3[1]) + (sv3[2] + sv3[3]));
;                         const float rs = __builtin_amdgcn_rsqf(st * (1.f / DM) + EPS);
;                         f32x4 a = acc[ai][0][m][0] * rs, b = acc[ai][0][m][1] * rs;
; #pragma unroll
;                         for (int i = 0; i < 4; ++i) { a[i] = logsig_f(a[i] + fb0[i]) * LOG2E; b[i] = logsig_f(b[i] + fb1[i]) * LOG2E; }
;                         *(f32x4*)(FF + (size_t)row * 8) = a; *(f32x4*)(FF + (size_t)row * 8 + 4) = b;
;                         asm volatile("" ::: "memory");
	v_mov_b32_e32 v26, v144
	v_mov_b32_e32 v27, v145
	v_mov_b32_e32 v28, v146
	v_mov_b32_e32 v29, v147
	v_mov_b32_e32 v30, v148
	v_mov_b32_e32 v31, v149
	v_mov_b32_e32 v32, v150
	v_mov_b32_e32 v33, v151
	v_mov_b32_e32 v34, v168
	v_mov_b32_e32 v35, v169
	v_mov_b32_e32 v36, v170
	v_mov_b32_e32 v37, v171
	v_mov_b32_e32 v38, v176
	v_mov_b32_e32 v39, v177
	v_mov_b32_e32 v40, v178
	v_mov_b32_e32 v41, v179
	v_mov_b32_e32 v42, v27
	v_mov_b32_e32 v43, v28
	v_mov_b32_e32 v27, v29
	v_mov_b32_e32 v28, v31
	v_mov_b32_e32 v29, v32
	v_mov_b32_e32 v31, v33
	v_pk_add_f32 v[26:27], v[42:43], v[26:27]
	v_pk_add_f32 v[28:29], v[28:29], v[30:31]
	v_pk_add_f32 v[26:27], v[26:27], v[26:27] op_sel:[0,1] op_sel_hi:[1,0]
	v_pk_add_f32 v[28:29], v[28:29], v[28:29] op_sel:[0,1] op_sel_hi:[1,0]
	v_add_f32_e32 v30, v34, v35
	v_add_f32_e32 v32, v36, v37
	v_mov_b32_e32 v27, v38
	v_mov_b32_e32 v29, v39
	v_mov_b32_e32 v31, v40
	v_mov_b32_e32 v33, v41
	v_pk_add_f32 v[26:27], v[26:27], v[28:29]
	v_pk_add_f32 v[28:29], v[30:31], v[32:33]
	s_nop 0
	v_pk_add_f32 v[26:27], v[26:27], v[28:29]
	s_nop 0
	v_add_f32_e32 v26, v26, v27
	v_fmamk_f32 v26, v26, 0x3a800000, v212
	v_rsq_f32_e32 v28, v26
	s_nop 0
	v_pk_mul_f32 v[20:21], v[20:21], v[28:29] op_sel_hi:[1,0]
	v_pk_mul_f32 v[26:27], v[22:23], v[28:29] op_sel_hi:[1,0]
	v_add_f32_e32 v22, v68, v20
	v_min_f32_e32 v20, 0, v22
	v_mul_f32_e64 v22, |v22|, s57
	v_exp_f32_e32 v22, v22
	v_pk_mul_f32 v[16:17], v[16:17], v[28:29] op_sel_hi:[1,0]
	v_pk_mul_f32 v[18:19], v[18:19], v[28:29] op_sel_hi:[1,0]
	v_add_f32_e32 v22, 1.0, v22
	v_log_f32_e32 v22, v22
	s_nop 0
	v_mul_f32_e32 v23, 0x3f317217, v22
	v_fma_f32 v23, v22, s52, -v23
	v_fmac_f32_e32 v23, 0x3377d1cf, v22
	v_fmac_f32_e32 v23, 0x3f317217, v22
	v_mov_b32_e32 v28, v23
	v_add_f32_e32 v22, v64, v16
	v_min_f32_e32 v16, 0, v22
	v_mul_f32_e64 v22, |v22|, s57
	v_exp_f32_e32 v22, v22
	s_nop 0
	v_add_f32_e32 v22, 1.0, v22
	v_log_f32_e32 v22, v22
	s_nop 0
	v_mul_f32_e32 v23, 0x3f317217, v22
	v_fma_f32 v23, v22, s52, -v23
	v_fmac_f32_e32 v23, 0x3377d1cf, v22
	v_fmac_f32_e32 v23, 0x3f317217, v22
	v_mov_b32_e32 v22, v23
	v_add_f32_e32 v23, v69, v21
	v_min_f32_e32 v21, 0, v23
	v_mul_f32_e64 v23, |v23|, s57
	v_exp_f32_e32 v23, v23
	s_nop 0
	v_add_f32_e32 v23, 1.0, v23
	v_log_f32_e32 v23, v23
	s_nop 0
	v_mul_f32_e32 v29, 0x3f317217, v23
	v_fma_f32 v29, v23, s52, -v29
	v_fmac_f32_e32 v29, 0x3377d1cf, v23
	v_fmac_f32_e32 v29, 0x3f317217, v23
	v_mov_b32_e32 v29, v29
	v_add_f32_e32 v23, v65, v17
	v_min_f32_e32 v17, 0, v23
	v_mul_f32_e64 v23, |v23|, s57
	v_exp_f32_e32 v23, v23
	v_pk_add_f32 v[20:21], v[20:21], v[28:29] neg_lo:[0,1] neg_hi:[0,1]
	v_add_f32_e32 v23, 1.0, v23
	v_log_f32_e32 v23, v23
	s_nop 0
	v_mul_f32_e32 v30, 0x3f317217, v23
	v_fma_f32 v30, v23, s52, -v30
	v_fmac_f32_e32 v30, 0x3377d1cf, v23
	v_fmac_f32_e32 v30, 0x3f317217, v23
	v_mov_b32_e32 v23, v30
	v_add_f32_e32 v30, v70, v26
	v_min_f32_e32 v26, 0, v30
	v_mul_f32_e64 v30, |v30|, s57
	v_exp_f32_e32 v30, v30
	v_pk_add_f32 v[16:17], v[16:17], v[22:23] neg_lo:[0,1] neg_hi:[0,1]
	v_add_f32_e32 v30, 1.0, v30
	v_pk_mul_f32 v[16:17], v[16:17], s[2:3] op_sel_hi:[1,0]
	s_nop 0
	v_log_f32_e32 v30, v30
	s_nop 0
	v_mul_f32_e32 v31, 0x3f317217, v30
	v_fma_f32 v31, v30, s52, -v31
	v_fmac_f32_e32 v31, 0x3377d1cf, v30
	v_fmac_f32_e32 v31, 0x3f317217, v30
	v_mov_b32_e32 v30, v31
	v_add_f32_e32 v31, v66, v18
	v_min_f32_e32 v18, 0, v31
	v_mul_f32_e64 v31, |v31|, s57
	v_exp_f32_e32 v31, v31
	s_nop 0
	v_add_f32_e32 v31, 1.0, v31
	v_log_f32_e32 v31, v31
	s_nop 0
	v_mul_f32_e32 v32, 0x3f317217, v31
	v_fma_f32 v32, v31, s52, -v32
	v_fmac_f32_e32 v32, 0x3377d1cf, v31
	v_fmac_f32_e32 v32, 0x3f317217, v31
	v_mov_b32_e32 v32, v32
	v_add_f32_e32 v31, v71, v27
	v_min_f32_e32 v27, 0, v31
	v_mul_f32_e64 v31, |v31|, s57
	v_exp_f32_e32 v31, v31
	s_nop 0
	v_add_f32_e32 v31, 1.0, v31
	v_log_f32_e32 v31, v31
	s_nop 0
	v_mul_f32_e32 v33, 0x3f317217, v31
	v_fma_f32 v33, v31, s52, -v33
	v_fmac_f32_e32 v33, 0x3377d1cf, v31
	v_fmac_f32_e32 v33, 0x3f317217, v31
	v_mov_b32_e32 v31, v33
	v_pk_add_f32 v[26:27], v[26:27], v[30:31] neg_lo:[0,1] neg_hi:[0,1]
	s_nop 0
	v_pk_mul_f32 v[28:29], v[26:27], s[2:3] op_sel_hi:[1,0]
	v_pk_mul_f32 v[26:27], v[20:21], s[2:3] op_sel_hi:[1,0]
	v_add_f32_e32 v20, v67, v19
	v_min_f32_e32 v19, 0, v20
	v_mul_f32_e64 v20, |v20|, s57
	v_exp_f32_e32 v20, v20
	s_nop 0
	v_add_f32_e32 v20, 1.0, v20
	v_log_f32_e32 v20, v20
	s_nop 0
	v_mul_f32_e32 v21, 0x3f317217, v20
	v_fma_f32 v21, v20, s52, -v21
	v_fmac_f32_e32 v21, 0x3377d1cf, v20
	v_fmac_f32_e32 v21, 0x3f317217, v20
	v_mov_b32_e32 v33, v21
	v_lshlrev_b64 v[20:21], 5, v[24:25]
	v_pk_add_f32 v[18:19], v[18:19], v[32:33] neg_lo:[0,1] neg_hi:[0,1]
	v_lshl_add_u64 v[20:21], s[42:43], 0, v[20:21]
	v_pk_mul_f32 v[18:19], v[18:19], s[2:3] op_sel_hi:[1,0]
	global_store_dwordx4 v[20:21], v[26:29], off
	global_store_dwordx4 v[20:21], v[16:19], off offset:16
	s_nop 1
	v_add_u32_e32 v16, 0xa0, v166
	v_ashrrev_i32_e32 v17, 31, v16
	v_lshlrev_b64 v[18:19], 6, v[16:17]
	v_lshl_add_u64 v[30:31], s[82:83], 0, v[18:19]
	s_nop 0
	s_waitcnt vmcnt(12)
; __device__ __forceinline__ float logsig_f(float x) { return fminf(x, 0.f) - __logf(1.f + __expf(-fabsf(x))); }
;     __device__ __forceinline__ void operator()(const f32x4 (&acc)[2][2][4][2], const pg8::Unit& u, int wr, int wc, int fr, int fq) const {
;     ...
;                     for (int m = 0; m < 4; ++m) {
;                         const int row = row0 + ai * 128 + m * 16;
;                         const f32x4 sv = *(const f32x4*)(ssq + (size_t)row * 16), sv1 = *(const f32x4*)(ssq + (size_t)row * 16 + 4), sv2 = *(const f32x4*)(ssq + (size_t)row * 16 + 8), sv3 = *(const f32x4*)(ssq + (size_t)row * 16 + 12);
;                         const float st = ((sv[0] + sv[1]) + (sv[2] + sv[3])) + ((sv1[0] + sv1[1]) + (sv1[2] + sv1[3])) + ((sv2[0] + sv2[1]) + (sv2[2] + sv2[3])) + ((sv3[0] + sv3[1]) + (sv3[2] + sv3[3]));
;                         const float rs = __builtin_amdgcn_rsqf(st * (1.f / DM) + EPS);
;                         f32x4 a = acc[ai][0][m][0] * rs, b = acc[ai][0][m][1] * rs;
; #pragma unroll
;                         for (int i = 0; i < 4; ++i) { a[i] = logsig_f(a[i] + fb0[i]) * LOG2E; b[i] = logsig_f(b[i] + fb1[i]) * LOG2E; }
;                         *(f32x4*)(FF + (size_t)row * 8) = a; *(f32x4*)(FF + (size_t)row * 8 + 4) = b;
;                         asm volatile("" ::: "memory");
	v_mov_b32_e32 v18, v180
	v_mov_b32_e32 v19, v181
	v_mov_b32_e32 v20, v182
	v_mov_b32_e32 v21, v183
	v_mov_b32_e32 v22, v184
	v_mov_b32_e32 v23, v185
	v_mov_b32_e32 v24, v186
	v_mov_b32_e32 v25, v187
	v_mov_b32_e32 v26, v188
	v_mov_b32_e32 v27, v189
	v_mov_b32_e32 v28, v190
	v_mov_b32_e32 v29, v191
	v_mov_b32_e32 v30, v204
	v_mov_b32_e32 v31, v205
	v_mov_b32_e32 v32, v206
	v_mov_b32_e32 v33, v207
	v_mov_b32_e32 v34, v19
	v_mov_b32_e32 v35, v20
	v_mov_b32_e32 v19, v21
	v_mov_b32_e32 v20, v23
	v_mov_b32_e32 v21, v24
	v_mov_b32_e32 v23, v25
	v_pk_add_f32 v[18:19], v[34:35], v[18:19]
	v_pk_add_f32 v[20:21], v[20:21], v[22:23]
	v_pk_add_f32 v[18:19], v[18:19], v[18:19] op_sel:[0,1] op_sel_hi:[1,0]
	v_pk_add_f32 v[20:21], v[20:21], v[20:21] op_sel:[0,1] op_sel_hi:[1,0]
	v_add_f32_e32 v22, v26, v27
	v_add_f32_e32 v24, v28, v29
	v_mov_b32_e32 v19, v30
	v_mov_b32_e32 v21, v31
	v_mov_b32_e32 v23, v32
	v_mov_b32_e32 v25, v33
	v_pk_add_f32 v[18:19], v[18:19], v[20:21]
	v_pk_add_f32 v[20:21], v[22:23], v[24:25]
	s_nop 0
	v_pk_add_f32 v[18:19], v[18:19], v[20:21]
	s_nop 0
	v_add_f32_e32 v18, v18, v19
	v_fmamk_f32 v18, v18, 0x3a800000, v212
	v_rsq_f32_e32 v20, v18
	s_nop 0
	v_pk_mul_f32 v[12:13], v[12:13], v[20:21] op_sel_hi:[1,0]
	v_pk_mul_f32 v[18:19], v[14:15], v[20:21] op_sel_hi:[1,0]
	v_add_f32_e32 v14, v68, v12
	v_min_f32_e32 v12, 0, v14
	v_mul_f32_e64 v14, |v14|, s57
	v_exp_f32_e32 v14, v14
	v_pk_mul_f32 v[8:9], v[8:9], v[20:21] op_sel_hi:[1,0]
	v_pk_mul_f32 v[10:11], v[10:11], v[20:21] op_sel_hi:[1,0]
	v_add_f32_e32 v14, 1.0, v14
	v_log_f32_e32 v14, v14
	s_nop 0
	v_mul_f32_e32 v15, 0x3f317217, v14
	v_fma_f32 v15, v14, s52, -v15
	v_fmac_f32_e32 v15, 0x3377d1cf, v14
	v_fmac_f32_e32 v15, 0x3f317217, v14
	v_mov_b32_e32 v20, v15
	v_add_f32_e32 v14, v64, v8
	v_min_f32_e32 v8, 0, v14
	v_mul_f32_e64 v14, |v14|, s57
	v_exp_f32_e32 v14, v14
	s_nop 0
	v_add_f32_e32 v14, 1.0, v14
	v_log_f32_e32 v14, v14
	s_nop 0
	v_mul_f32_e32 v15, 0x3f317217, v14
	v_fma_f32 v15, v14, s52, -v15
	v_fmac_f32_e32 v15, 0x3377d1cf, v14
	v_fmac_f32_e32 v15, 0x3f317217, v14
	v_mov_b32_e32 v14, v15
	v_add_f32_e32 v15, v69, v13
	v_min_f32_e32 v13, 0, v15
	v_mul_f32_e64 v15, |v15|, s57
	v_exp_f32_e32 v15, v15
	s_nop 0
	v_add_f32_e32 v15, 1.0, v15
	v_log_f32_e32 v15, v15
	s_nop 0
	v_mul_f32_e32 v21, 0x3f317217, v15
	v_fma_f32 v21, v15, s52, -v21
	v_fmac_f32_e32 v21, 0x3377d1cf, v15
	v_fmac_f32_e32 v21, 0x3f317217, v15
	v_mov_b32_e32 v21, v21
	v_add_f32_e32 v15, v65, v9
	v_min_f32_e32 v9, 0, v15
	v_mul_f32_e64 v15, |v15|, s57
	v_exp_f32_e32 v15, v15
	v_pk_add_f32 v[12:13], v[12:13], v[20:21] neg_lo:[0,1] neg_hi:[0,1]
	v_add_f32_e32 v15, 1.0, v15
	v_log_f32_e32 v15, v15
	s_nop 0
	v_mul_f32_e32 v22, 0x3f317217, v15
	v_fma_f32 v22, v15, s52, -v22
	v_fmac_f32_e32 v22, 0x3377d1cf, v15
	v_fmac_f32_e32 v22, 0x3f317217, v15
	v_mov_b32_e32 v15, v22
	v_add_f32_e32 v22, v70, v18
	v_min_f32_e32 v18, 0, v22
	v_mul_f32_e64 v22, |v22|, s57
	v_exp_f32_e32 v22, v22
	v_pk_add_f32 v[8:9], v[8:9], v[14:15] neg_lo:[0,1] neg_hi:[0,1]
	v_add_f32_e32 v22, 1.0, v22
	v_pk_mul_f32 v[8:9], v[8:9], s[2:3] op_sel_hi:[1,0]
	s_nop 0
	v_log_f32_e32 v22, v22
	s_nop 0
	v_mul_f32_e32 v23, 0x3f317217, v22
	v_fma_f32 v23, v22, s52, -v23
	v_fmac_f32_e32 v23, 0x3377d1cf, v22
	v_fmac_f32_e32 v23, 0x3f317217, v22
	v_mov_b32_e32 v22, v23
	v_add_f32_e32 v23, v66, v10
	v_min_f32_e32 v10, 0, v23
	v_mul_f32_e64 v23, |v23|, s57
	v_exp_f32_e32 v23, v23
	s_nop 0
	v_add_f32_e32 v23, 1.0, v23
	v_log_f32_e32 v23, v23
	s_nop 0
	v_mul_f32_e32 v24, 0x3f317217, v23
	v_fma_f32 v24, v23, s52, -v24
	v_fmac_f32_e32 v24, 0x3377d1cf, v23
	v_fmac_f32_e32 v24, 0x3f317217, v23
	v_mov_b32_e32 v24, v24
	v_add_f32_e32 v23, v71, v19
	v_min_f32_e32 v19, 0, v23
	v_mul_f32_e64 v23, |v23|, s57
	v_exp_f32_e32 v23, v23
	s_nop 0
	v_add_f32_e32 v23, 1.0, v23
	v_log_f32_e32 v23, v23
	s_nop 0
	v_mul_f32_e32 v25, 0x3f317217, v23
	v_fma_f32 v25, v23, s52, -v25
	v_fmac_f32_e32 v25, 0x3377d1cf, v23
	v_fmac_f32_e32 v25, 0x3f317217, v23
	v_mov_b32_e32 v23, v25
	v_pk_add_f32 v[18:19], v[18:19], v[22:23] neg_lo:[0,1] neg_hi:[0,1]
	s_nop 0
	v_pk_mul_f32 v[20:21], v[18:19], s[2:3] op_sel_hi:[1,0]
	v_pk_mul_f32 v[18:19], v[12:13], s[2:3] op_sel_hi:[1,0]
	v_add_f32_e32 v12, v67, v11
	v_min_f32_e32 v11, 0, v12
	v_mul_f32_e64 v12, |v12|, s57
	v_exp_f32_e32 v12, v12
	s_nop 0
	v_add_f32_e32 v12, 1.0, v12
	v_log_f32_e32 v12, v12
	s_nop 0
	v_mul_f32_e32 v13, 0x3f317217, v12
	v_fma_f32 v13, v12, s52, -v13
	v_fmac_f32_e32 v13, 0x3377d1cf, v12
	v_fmac_f32_e32 v13, 0x3f317217, v12
	v_mov_b32_e32 v25, v13
	v_lshlrev_b64 v[12:13], 5, v[16:17]
	v_pk_add_f32 v[10:11], v[10:11], v[24:25] neg_lo:[0,1] neg_hi:[0,1]
	v_lshl_add_u64 v[12:13], s[42:43], 0, v[12:13]
	v_pk_mul_f32 v[10:11], v[10:11], s[2:3] op_sel_hi:[1,0]
	global_store_dwordx4 v[12:13], v[18:21], off
	global_store_dwordx4 v[12:13], v[8:11], off offset:16
	s_nop 1
	v_add_u32_e32 v8, 0xb0, v166
	v_ashrrev_i32_e32 v9, 31, v8
	v_lshlrev_b64 v[10:11], 6, v[8:9]
	v_lshl_add_u64 v[22:23], s[82:83], 0, v[10:11]
	s_nop 0
	s_waitcnt vmcnt(8)
; __device__ __forceinline__ float logsig_f(float x) { return fminf(x, 0.f) - __logf(1.f + __expf(-fabsf(x))); }
;     __device__ __forceinline__ void operator()(const f32x4 (&acc)[2][2][4][2], const pg8::Unit& u, int wr, int wc, int fr, int fq) const {
;     ...
;                     for (int m = 0; m < 4; ++m) {
;                         const int row = row0 + ai * 128 + m * 16;
;                         const f32x4 sv = *(const f32x4*)(ssq + (size_t)row * 16), sv1 = *(const f32x4*)(ssq + (size_t)row * 16 + 4), sv2 = *(const f32x4*)(ssq + (size_t)row * 16 + 8), sv3 = *(const f32x4*)(ssq + (size_t)row * 16 + 12);
;                         const float st = ((sv[0] + sv[1]) + (sv[2] + sv[3])) + ((sv1[0] + sv1[1]) + (sv1[2] + sv1[3])) + ((sv2[0] + sv2[1]) + (sv2[2] + sv2[3])) + ((sv3[0] + sv3[1]) + (sv3[2] + sv3[3]));
;                         const float rs = __builtin_amdgcn_rsqf(st * (1.f / DM) + EPS);
;                         f32x4 a = acc[ai][0][m][0] * rs, b = acc[ai][0][m][1] * rs;
; #pragma unroll
;                         for (int i = 0; i < 4; ++i) { a[i] = logsig_f(a[i] + fb0[i]) * LOG2E; b[i] = logsig_f(b[i] + fb1[i]) * LOG2E; }
;                         *(f32x4*)(FF + (size_t)row * 8) = a; *(f32x4*)(FF + (size_t)row * 8 + 4) = b;
;                         asm volatile("" ::: "memory");
	v_mov_b32_e32 v10, v208
	v_mov_b32_e32 v11, v209
	v_mov_b32_e32 v12, v210
	v_mov_b32_e32 v13, v211
	v_mov_b32_e32 v14, v224
	v_mov_b32_e32 v15, v225
	v_mov_b32_e32 v16, v226
	v_mov_b32_e32 v17, v227
	v_mov_b32_e32 v18, v228
	v_mov_b32_e32 v19, v229
	v_mov_b32_e32 v20, v230
	v_mov_b32_e32 v21, v231
	v_mov_b32_e32 v22, v232
	v_mov_b32_e32 v23, v233
	v_mov_b32_e32 v24, v234
	v_mov_b32_e32 v25, v235
	v_mov_b32_e32 v26, v11
	v_mov_b32_e32 v27, v12
	v_mov_b32_e32 v11, v13
	v_mov_b32_e32 v12, v15
	v_mov_b32_e32 v13, v16
	v_mov_b32_e32 v15, v17
	v_pk_add_f32 v[10:11], v[26:27], v[10:11]
	v_pk_add_f32 v[12:13], v[12:13], v[14:15]
	v_pk_add_f32 v[10:11], v[10:11], v[10:11] op_sel:[0,1] op_sel_hi:[1,0]
	v_pk_add_f32 v[12:13], v[12:13], v[12:13] op_sel:[0,1] op_sel_hi:[1,0]
	v_add_f32_e32 v14, v18, v19
	v_add_f32_e32 v16, v20, v21
	v_mov_b32_e32 v11, v22
	v_mov_b32_e32 v13, v23
	v_mov_b32_e32 v15, v24
	v_mov_b32_e32 v17, v25
	v_pk_add_f32 v[10:11], v[10:11], v[12:13]
	v_pk_add_f32 v[12:13], v[14:15], v[16:17]
	s_nop 0
	v_pk_add_f32 v[10:11], v[10:11], v[12:13]
	s_nop 0
	v_add_f32_e32 v10, v10, v11
	v_fmamk_f32 v10, v10, 0x3a800000, v212
	v_rsq_f32_e32 v12, v10
	s_nop 0
	v_pk_mul_f32 v[4:5], v[4:5], v[12:13] op_sel_hi:[1,0]
	v_pk_mul_f32 v[10:11], v[6:7], v[12:13] op_sel_hi:[1,0]
	v_add_f32_e32 v6, v68, v4
	v_min_f32_e32 v4, 0, v6
	v_mul_f32_e64 v6, |v6|, s57
	v_exp_f32_e32 v6, v6
	v_pk_mul_f32 v[0:1], v[0:1], v[12:13] op_sel_hi:[1,0]
	v_pk_mul_f32 v[2:3], v[2:3], v[12:13] op_sel_hi:[1,0]
	v_add_f32_e32 v6, 1.0, v6
	v_log_f32_e32 v6, v6
	s_nop 0
	v_mul_f32_e32 v7, 0x3f317217, v6
	v_fma_f32 v7, v6, s52, -v7
	v_fmac_f32_e32 v7, 0x3377d1cf, v6
	v_fmac_f32_e32 v7, 0x3f317217, v6
	v_mov_b32_e32 v12, v7
	v_add_f32_e32 v6, v64, v0
	v_min_f32_e32 v0, 0, v6
	v_mul_f32_e64 v6, |v6|, s57
	v_exp_f32_e32 v6, v6
	s_nop 0
	v_add_f32_e32 v6, 1.0, v6
	v_log_f32_e32 v6, v6
	s_nop 0
	v_mul_f32_e32 v7, 0x3f317217, v6
	v_fma_f32 v7, v6, s52, -v7
	v_fmac_f32_e32 v7, 0x3377d1cf, v6
	v_fmac_f32_e32 v7, 0x3f317217, v6
	v_mov_b32_e32 v6, v7
	v_add_f32_e32 v7, v69, v5
	v_min_f32_e32 v5, 0, v7
	v_mul_f32_e64 v7, |v7|, s57
	v_exp_f32_e32 v7, v7
	s_nop 0
	v_add_f32_e32 v7, 1.0, v7
	v_log_f32_e32 v7, v7
	s_nop 0
	v_mul_f32_e32 v13, 0x3f317217, v7
	v_fma_f32 v13, v7, s52, -v13
	v_fmac_f32_e32 v13, 0x3377d1cf, v7
	v_fmac_f32_e32 v13, 0x3f317217, v7
	v_mov_b32_e32 v13, v13
	v_add_f32_e32 v7, v65, v1
	v_min_f32_e32 v1, 0, v7
	v_mul_f32_e64 v7, |v7|, s57
	v_exp_f32_e32 v7, v7
	v_pk_add_f32 v[4:5], v[4:5], v[12:13] neg_lo:[0,1] neg_hi:[0,1]
	v_add_f32_e32 v7, 1.0, v7
	v_log_f32_e32 v7, v7
	s_nop 0
	v_mul_f32_e32 v14, 0x3f317217, v7
	v_fma_f32 v14, v7, s52, -v14
	v_fmac_f32_e32 v14, 0x3377d1cf, v7
	v_fmac_f32_e32 v14, 0x3f317217, v7
	v_mov_b32_e32 v7, v14
	v_add_f32_e32 v14, v70, v10
	v_min_f32_e32 v10, 0, v14
	v_mul_f32_e64 v14, |v14|, s57
	v_exp_f32_e32 v14, v14
	v_pk_add_f32 v[0:1], v[0:1], v[6:7] neg_lo:[0,1] neg_hi:[0,1]
	v_add_f32_e32 v14, 1.0, v14
	v_pk_mul_f32 v[0:1], v[0:1], s[2:3] op_sel_hi:[1,0]
	s_nop 0
	v_log_f32_e32 v14, v14
	s_nop 0
	v_mul_f32_e32 v15, 0x3f317217, v14
	v_fma_f32 v15, v14, s52, -v15
	v_fmac_f32_e32 v15, 0x3377d1cf, v14
	v_fmac_f32_e32 v15, 0x3f317217, v14
	v_mov_b32_e32 v14, v15
	v_add_f32_e32 v15, v66, v2
	v_min_f32_e32 v2, 0, v15
	v_mul_f32_e64 v15, |v15|, s57
	v_exp_f32_e32 v15, v15
	s_nop 0
	v_add_f32_e32 v15, 1.0, v15
	v_log_f32_e32 v15, v15
	s_nop 0
	v_mul_f32_e32 v16, 0x3f317217, v15
	v_fma_f32 v16, v15, s52, -v16
	v_fmac_f32_e32 v16, 0x3377d1cf, v15
	v_fmac_f32_e32 v16, 0x3f317217, v15
	v_mov_b32_e32 v16, v16
	v_add_f32_e32 v15, v71, v11
	v_min_f32_e32 v11, 0, v15
	v_mul_f32_e64 v15, |v15|, s57
	v_exp_f32_e32 v15, v15
	s_nop 0
	v_add_f32_e32 v15, 1.0, v15
	v_log_f32_e32 v15, v15
	s_nop 0
	v_mul_f32_e32 v17, 0x3f317217, v15
	v_fma_f32 v17, v15, s52, -v17
	v_fmac_f32_e32 v17, 0x3377d1cf, v15
	v_fmac_f32_e32 v17, 0x3f317217, v15
	v_mov_b32_e32 v15, v17
	v_pk_add_f32 v[10:11], v[10:11], v[14:15] neg_lo:[0,1] neg_hi:[0,1]
	s_nop 0
	v_pk_mul_f32 v[12:13], v[10:11], s[2:3] op_sel_hi:[1,0]
	v_pk_mul_f32 v[10:11], v[4:5], s[2:3] op_sel_hi:[1,0]
	v_add_f32_e32 v4, v67, v3
	v_min_f32_e32 v3, 0, v4
	v_mul_f32_e64 v4, |v4|, s57
	v_exp_f32_e32 v4, v4
	s_nop 0
	v_add_f32_e32 v4, 1.0, v4
	v_log_f32_e32 v4, v4
	s_nop 0
	v_mul_f32_e32 v5, 0x3f317217, v4
	v_fma_f32 v5, v4, s52, -v5
	v_fmac_f32_e32 v5, 0x3377d1cf, v4
	v_fmac_f32_e32 v5, 0x3f317217, v4
	v_mov_b32_e32 v17, v5
	v_lshlrev_b64 v[4:5], 5, v[8:9]
	v_pk_add_f32 v[2:3], v[2:3], v[16:17] neg_lo:[0,1] neg_hi:[0,1]
	v_lshl_add_u64 v[4:5], s[42:43], 0, v[4:5]
	v_pk_mul_f32 v[2:3], v[2:3], s[2:3] op_sel_hi:[1,0]
	global_store_dwordx4 v[4:5], v[10:13], off
	global_store_dwordx4 v[4:5], v[0:3], off offset:16
